# P2y load balance: GLA sample iterations moved from workgroups with long RWKV rebuilds (blockIdx&3 = 3: none, = 2: one) to those with short ones (= 0: four, = 1: three)
# speedup vs baseline: 1.0081x; 1.0081x over previous
.LBB0_703:
	s_cmpk_lt_i32 s50, 0x400
	s_cbranch_scc0 .Lp2y_samp
	s_add_i32 s50, s50, s80
	s_add_i32 s97, s97, s80
	s_add_i32 s83, s83, s81
	s_add_i32 s82, s82, s80
	s_cmpk_lt_i32 s50, 0x400
	s_cbranch_scc1 .LBB0_704
	s_mov_b32 s100, 0
	s_mov_b32 s101, s50
	s_and_b32 s0, s50, 3
	s_cmp_eq_u32 s0, 3
	s_cbranch_scc1 .LBB0_854
	s_branch .LBB0_704
.Lp2y_samp:
	s_add_i32 s100, s100, 1
	s_and_b32 s0, s101, 3
	s_cmp_eq_u32 s0, 2
	s_cbranch_scc1 .LBB0_854
	s_cmp_eq_u32 s100, 1
	s_cbranch_scc0 .Lp2y_s2
	s_add_i32 s50, s101, 0x100
	s_branch .LBB0_704
.Lp2y_s2:
	s_cmp_eq_u32 s100, 2
	s_cbranch_scc0 .Lp2y_s3
	s_cmp_eq_u32 s0, 0
	s_cselect_b32 s1, 3, 0x101
	s_add_i32 s50, s101, s1
	s_branch .LBB0_704
.Lp2y_s3:
	s_cmp_eq_u32 s100, 3
	s_cbranch_scc0 .LBB0_854
	s_cmp_eq_u32 s0, 0
	s_cbranch_scc0 .LBB0_854
	s_add_i32 s50, s101, 0x103
	s_branch .LBB0_704

	.amdhsa_kernel _Z14fwd_megakernel4Args
		.amdhsa_group_segment_fixed_size 0
		.amdhsa_private_segment_fixed_size 0
		.amdhsa_kernarg_size 520
		.amdhsa_user_sgpr_count 2
		.amdhsa_user_sgpr_dispatch_ptr 0
		.amdhsa_user_sgpr_queue_ptr 0
		.amdhsa_user_sgpr_kernarg_segment_ptr 1
		.amdhsa_user_sgpr_dispatch_id 0
		.amdhsa_user_sgpr_kernarg_preload_length 0
		.amdhsa_user_sgpr_kernarg_preload_offset 0
		.amdhsa_user_sgpr_private_segment_size 0
		.amdhsa_uses_dynamic_stack 0
		.amdhsa_enable_private_segment 0
		.amdhsa_system_sgpr_workgroup_id_x 1
		.amdhsa_system_sgpr_workgroup_id_y 0
		.amdhsa_system_sgpr_workgroup_id_z 0
		.amdhsa_system_sgpr_workgroup_info 0
		.amdhsa_system_vgpr_workitem_id 2
		.amdhsa_next_free_vgpr 256
		.amdhsa_next_free_sgpr 102
		.amdhsa_accum_offset 256
		.amdhsa_reserve_vcc 1
		.amdhsa_float_round_mode_32 0
		.amdhsa_float_round_mode_16_64 0
		.amdhsa_float_denorm_mode_32 3
		.amdhsa_float_denorm_mode_16_64 3
		.amdhsa_dx10_clamp 1
		.amdhsa_ieee_mode 1
		.amdhsa_fp16_overflow 0
		.amdhsa_tg_split 0
		.amdhsa_exception_fp_ieee_invalid_op 0
		.amdhsa_exception_fp_denorm_src 0
		.amdhsa_exception_fp_ieee_div_zero 0
		.amdhsa_exception_fp_ieee_overflow 0
		.amdhsa_exception_fp_ieee_underflow 0
		.amdhsa_exception_fp_ieee_inexact 0
		.amdhsa_exception_int_div_zero 0
	.end_amdhsa_kernel

amdhsa.kernels:
  - .agpr_count:     0
    .args:
      - .offset:         0
        .size:           264
        .value_kind:     by_value
      - .offset:         264
        .size:           4
        .value_kind:     hidden_block_count_x
      - .offset:         268
        .size:           4
        .value_kind:     hidden_block_count_y
      - .offset:         272
        .size:           4
        .value_kind:     hidden_block_count_z
      - .offset:         276
        .size:           2
        .value_kind:     hidden_group_size_x
      - .offset:         278
        .size:           2
        .value_kind:     hidden_group_size_y
      - .offset:         280
        .size:           2
        .value_kind:     hidden_group_size_z
      - .offset:         282
        .size:           2
        .value_kind:     hidden_remainder_x
      - .offset:         284
        .size:           2
        .value_kind:     hidden_remainder_y
      - .offset:         286
        .size:           2
        .value_kind:     hidden_remainder_z
      - .offset:         304
        .size:           8
        .value_kind:     hidden_global_offset_x
      - .offset:         312
        .size:           8
        .value_kind:     hidden_global_offset_y
      - .offset:         320
        .size:           8
        .value_kind:     hidden_global_offset_z
      - .offset:         328
        .size:           2
        .value_kind:     hidden_grid_dims
      - .offset:         352
        .size:           8
        .value_kind:     hidden_multigrid_sync_arg
      - .offset:         384
        .size:           4
        .value_kind:     hidden_dynamic_lds_size
    .group_segment_fixed_size: 0
    .kernarg_segment_align: 8
    .kernarg_segment_size: 520
    .language:       OpenCL C
    .language_version:
      - 2
      - 0
    .max_flat_workgroup_size: 512
    .name:           _Z14fwd_megakernel4Args
    .private_segment_fixed_size: 0
    .sgpr_count:     108
    .sgpr_spill_count: 159
    .symbol:         _Z14fwd_megakernel4Args.kd
    .uniform_work_group_size: 1
    .uses_dynamic_stack: false
    .vgpr_count:     256
    .vgpr_spill_count: 0
    .wavefront_size: 64
